# final RMSNorm: 4 rows batched per trip with lane-contiguous 16-byte stores
# speedup vs baseline: 1.0046x; 1.0046x over previous
; __device__ __forceinline__ float row_rstd(const float* ss, int row) {
;     const f32x4* p = (const f32x4*)(ss + (size_t)row * 16); const f32x4 a = p[0], b = p[1], c = p[2], d = p[3];
;     const float s = (((a[0] + a[1]) + (a[2] + a[3])) + ((b[0] + b[1]) + (b[2] + b[3]))) + (((c[0] + c[1]) + (c[2] + c[3])) + ((d[0] + d[1]) + (d[2] + d[3])));
;     return __builtin_amdgcn_rsqf(s * (1.f / DM) + EPS);
; }
; __global__ void __launch_bounds__(NWAVES * 64, 2) mk_fwd(Args args) {
;     ...
;     if (IN(9)) {
;         PHASE_IDS
;         const float* ss = (const float*)(ws + WS_SS3);
;         const bf16_t* X3 = (const bf16_t*)(ws + WS_XN);
;         for (int m = gw; m < MT; m += NGW) { const float rs = row_rstd(ss, m);
;             const u32x4* xr = (const u32x4*)(X3 + (size_t)m * DM) + lane; f32x4* orow = (f32x4*)(P.out + (size_t)m * DM); const f32x4* gr = (const f32x4*)P.g_fin;
; #pragma unroll
;             for (int j = 0; j < 2; ++j) { const u32x4 w = xr[64 * j]; const int c4 = (64 * j + lane) * 2; const f32x4 ga = gr[c4], gb = gr[c4 + 1];
;                 f32x4 a, b2; a[0] = bflo(w.x) * rs * ga[0]; a[1] = bfhi(w.x) * rs * ga[1]; a[2] = bflo(w.y) * rs * ga[2]; a[3] = bfhi(w.y) * rs * ga[3];
;                 b2[0] = bflo(w.z) * rs * gb[0]; b2[1] = bfhi(w.z) * rs * gb[1]; b2[2] = bflo(w.w) * rs * gb[2]; b2[3] = bfhi(w.w) * rs * gb[3];
;                 orow[c4] = a; orow[c4 + 1] = b2; } }
;     }
.LBB0_1151:
	s_cmp_lt_i32 s70, 10
	s_cselect_b64 s[2:3], -1, 0
	s_and_b64 s[0:1], s[2:3], s[0:1]
	s_andn2_b64 vcc, exec, s[0:1]
	s_cbranch_vccnz .LBB0_1155
	s_lshl_b32 s1, s63, 3
	v_readfirstlane_b32 s0, v185
	s_ashr_i32 s0, s0, 6
	s_add_i32 s8, s0, s1
	v_and_b32_e32 v6, 63, v185
	v_lshlrev_b32_e32 v0, 4, v6
	v_lshlrev_b32_e32 v1, 3, v6
	v_mov_b32_e32 v2, 0
	v_mov_b32_e32 v8, 0x358637bd
	s_add_u32 s12, s68, 0x400000
	s_addc_u32 s13, s69, 0
	s_add_u32 s14, s68, 0x3800000
	s_addc_u32 s15, s69, 0
	s_mul_i32 s9, s58, 3
	s_add_i32 s9, s9, s8
	s_cmpk_gt_i32 s9, 0x3fff
	s_cbranch_scc1 .Lp9_tail
	global_load_dwordx4 v[10:13], v0, s[64:65]
	global_load_dwordx4 v[14:17], v0, s[64:65] offset:1024
	global_load_dwordx4 v[18:21], v0, s[64:65] offset:2048
	global_load_dwordx4 v[22:25], v0, s[64:65] offset:3072
.Lp9_loop:
	s_mov_b32 s16, s8
	s_lshl_b32 s17, s16, 6
	s_add_u32 s18, s12, s17
	s_addc_u32 s19, s13, 0
	global_load_dwordx4 v[32:35], v2, s[18:19]
	global_load_dwordx4 v[36:39], v2, s[18:19] offset:16
	global_load_dwordx4 v[40:43], v2, s[18:19] offset:32
	global_load_dwordx4 v[44:47], v2, s[18:19] offset:48
	s_lshl_b32 s17, s16, 11
	s_add_u32 s18, s14, s17
	s_addc_u32 s19, s15, 0
	global_load_dwordx2 v[48:49], v1, s[18:19]
	global_load_dwordx2 v[50:51], v1, s[18:19] offset:512
	global_load_dwordx2 v[52:53], v1, s[18:19] offset:1024
	global_load_dwordx2 v[54:55], v1, s[18:19] offset:1536
	s_add_i32 s16, s16, s58
	s_lshl_b32 s17, s16, 6
	s_add_u32 s18, s12, s17
	s_addc_u32 s19, s13, 0
	global_load_dwordx4 v[56:59], v2, s[18:19]
	global_load_dwordx4 v[60:63], v2, s[18:19] offset:16
	global_load_dwordx4 v[64:67], v2, s[18:19] offset:32
	global_load_dwordx4 v[68:71], v2, s[18:19] offset:48
	s_lshl_b32 s17, s16, 11
	s_add_u32 s18, s14, s17
	s_addc_u32 s19, s15, 0
	global_load_dwordx2 v[72:73], v1, s[18:19]
	global_load_dwordx2 v[74:75], v1, s[18:19] offset:512
	global_load_dwordx2 v[76:77], v1, s[18:19] offset:1024
	global_load_dwordx2 v[78:79], v1, s[18:19] offset:1536
	s_add_i32 s16, s16, s58
	s_lshl_b32 s17, s16, 6
	s_add_u32 s18, s12, s17
	s_addc_u32 s19, s13, 0
	global_load_dwordx4 v[80:83], v2, s[18:19]
	global_load_dwordx4 v[84:87], v2, s[18:19] offset:16
	global_load_dwordx4 v[88:91], v2, s[18:19] offset:32
	global_load_dwordx4 v[92:95], v2, s[18:19] offset:48
	s_lshl_b32 s17, s16, 11
	s_add_u32 s18, s14, s17
	s_addc_u32 s19, s15, 0
	global_load_dwordx2 v[96:97], v1, s[18:19]
	global_load_dwordx2 v[98:99], v1, s[18:19] offset:512
	global_load_dwordx2 v[100:101], v1, s[18:19] offset:1024
	global_load_dwordx2 v[102:103], v1, s[18:19] offset:1536
	s_add_i32 s16, s16, s58
	s_lshl_b32 s17, s16, 6
	s_add_u32 s18, s12, s17
	s_addc_u32 s19, s13, 0
	global_load_dwordx4 v[104:107], v2, s[18:19]
	global_load_dwordx4 v[108:111], v2, s[18:19] offset:16
	global_load_dwordx4 v[112:115], v2, s[18:19] offset:32
	global_load_dwordx4 v[116:119], v2, s[18:19] offset:48
	s_lshl_b32 s17, s16, 11
	s_add_u32 s18, s14, s17
	s_addc_u32 s19, s15, 0
	global_load_dwordx2 v[120:121], v1, s[18:19]
	global_load_dwordx2 v[122:123], v1, s[18:19] offset:512
	global_load_dwordx2 v[124:125], v1, s[18:19] offset:1024
	global_load_dwordx2 v[126:127], v1, s[18:19] offset:1536
	s_mov_b32 s16, s8
	s_waitcnt vmcnt(24)
	v_add_f32_e32 v32, v32, v33
	v_add_f32_e32 v34, v34, v35
	v_add_f32_e32 v36, v36, v37
	v_add_f32_e32 v38, v38, v39
	v_add_f32_e32 v40, v40, v41
	v_add_f32_e32 v42, v42, v43
	v_add_f32_e32 v44, v44, v45
	v_add_f32_e32 v46, v46, v47
	v_add_f32_e32 v32, v32, v34
	v_add_f32_e32 v36, v36, v38
	v_add_f32_e32 v40, v40, v42
	v_add_f32_e32 v44, v44, v46
	v_add_f32_e32 v32, v32, v36
	v_add_f32_e32 v40, v40, v44
	v_add_f32_e32 v32, v32, v40
	v_fmamk_f32 v32, v32, 0x3a800000, v8
	v_rsq_f32_e32 v9, v32
	v_lshlrev_b32_e32 v128, 16, v48
	v_and_b32_e32 v129, 0xffff0000, v48
	v_lshlrev_b32_e32 v130, 16, v49
	v_and_b32_e32 v131, 0xffff0000, v49
	v_lshlrev_b32_e32 v132, 16, v50
	v_and_b32_e32 v133, 0xffff0000, v50
	v_lshlrev_b32_e32 v134, 16, v51
	v_and_b32_e32 v135, 0xffff0000, v51
	v_lshlrev_b32_e32 v136, 16, v52
	v_and_b32_e32 v137, 0xffff0000, v52
	v_lshlrev_b32_e32 v138, 16, v53
	v_and_b32_e32 v139, 0xffff0000, v53
	v_lshlrev_b32_e32 v140, 16, v54
	v_and_b32_e32 v141, 0xffff0000, v54
	v_lshlrev_b32_e32 v142, 16, v55
	v_and_b32_e32 v143, 0xffff0000, v55
	v_mul_f32_e32 v128, v9, v128
	v_mul_f32_e32 v129, v9, v129
	v_mul_f32_e32 v130, v9, v130
	v_mul_f32_e32 v131, v9, v131
	v_mul_f32_e32 v132, v9, v132
	v_mul_f32_e32 v133, v9, v133
	v_mul_f32_e32 v134, v9, v134
	v_mul_f32_e32 v135, v9, v135
	v_mul_f32_e32 v136, v9, v136
	v_mul_f32_e32 v137, v9, v137
	v_mul_f32_e32 v138, v9, v138
	v_mul_f32_e32 v139, v9, v139
	v_mul_f32_e32 v140, v9, v140
	v_mul_f32_e32 v141, v9, v141
	v_mul_f32_e32 v142, v9, v142
	v_mul_f32_e32 v143, v9, v143
	v_mul_f32_e32 v128, v10, v128
	v_mul_f32_e32 v129, v11, v129
	v_mul_f32_e32 v130, v12, v130
	v_mul_f32_e32 v131, v13, v131
	v_mul_f32_e32 v132, v14, v132
	v_mul_f32_e32 v133, v15, v133
	v_mul_f32_e32 v134, v16, v134
	v_mul_f32_e32 v135, v17, v135
	v_mul_f32_e32 v136, v18, v136
	v_mul_f32_e32 v137, v19, v137
	v_mul_f32_e32 v138, v20, v138
	v_mul_f32_e32 v139, v21, v139
	v_mul_f32_e32 v140, v22, v140
	v_mul_f32_e32 v141, v23, v141
	v_mul_f32_e32 v142, v24, v142
	v_mul_f32_e32 v143, v25, v143
	s_lshl_b32 s17, s16, 12
	s_add_u32 s18, s66, s17
	s_addc_u32 s19, s67, 0
	global_store_dwordx4 v0, v[128:131], s[18:19]
	global_store_dwordx4 v0, v[132:135], s[18:19] offset:1024
	global_store_dwordx4 v0, v[136:139], s[18:19] offset:2048
	global_store_dwordx4 v0, v[140:143], s[18:19] offset:3072
	s_add_i32 s16, s16, s58
	s_waitcnt vmcnt(20)
; __device__ __forceinline__ float row_rstd(const float* ss, int row) {
;     const f32x4* p = (const f32x4*)(ss + (size_t)row * 16); const f32x4 a = p[0], b = p[1], c = p[2], d = p[3];
;     const float s = (((a[0] + a[1]) + (a[2] + a[3])) + ((b[0] + b[1]) + (b[2] + b[3]))) + (((c[0] + c[1]) + (c[2] + c[3])) + ((d[0] + d[1]) + (d[2] + d[3])));
;     return __builtin_amdgcn_rsqf(s * (1.f / DM) + EPS);
; }
; __global__ void __launch_bounds__(NWAVES * 64, 2) mk_fwd(Args args) {
;     ...
;         for (int m = gw; m < MT; m += NGW) { const float rs = row_rstd(ss, m);
;             const u32x4* xr = (const u32x4*)(X3 + (size_t)m * DM) + lane; f32x4* orow = (f32x4*)(P.out + (size_t)m * DM); const f32x4* gr = (const f32x4*)P.g_fin;
; #pragma unroll
;             for (int j = 0; j < 2; ++j) { const u32x4 w = xr[64 * j]; const int c4 = (64 * j + lane) * 2; const f32x4 ga = gr[c4], gb = gr[c4 + 1];
;                 f32x4 a, b2; a[0] = bflo(w.x) * rs * ga[0]; a[1] = bfhi(w.x) * rs * ga[1]; a[2] = bflo(w.y) * rs * ga[2]; a[3] = bfhi(w.y) * rs * ga[3];
;                 b2[0] = bflo(w.z) * rs * gb[0]; b2[1] = bfhi(w.z) * rs * gb[1]; b2[2] = bflo(w.w) * rs * gb[2]; b2[3] = bfhi(w.w) * rs * gb[3];
;                 orow[c4] = a; orow[c4 + 1] = b2; } }
	v_add_f32_e32 v56, v56, v57
	v_add_f32_e32 v58, v58, v59
	v_add_f32_e32 v60, v60, v61
	v_add_f32_e32 v62, v62, v63
	v_add_f32_e32 v64, v64, v65
	v_add_f32_e32 v66, v66, v67
	v_add_f32_e32 v68, v68, v69
	v_add_f32_e32 v70, v70, v71
	v_add_f32_e32 v56, v56, v58
	v_add_f32_e32 v60, v60, v62
	v_add_f32_e32 v64, v64, v66
	v_add_f32_e32 v68, v68, v70
	v_add_f32_e32 v56, v56, v60
	v_add_f32_e32 v64, v64, v68
	v_add_f32_e32 v56, v56, v64
	v_fmamk_f32 v56, v56, 0x3a800000, v8
	v_rsq_f32_e32 v9, v56
	v_lshlrev_b32_e32 v128, 16, v72
	v_and_b32_e32 v129, 0xffff0000, v72
	v_lshlrev_b32_e32 v130, 16, v73
	v_and_b32_e32 v131, 0xffff0000, v73
	v_lshlrev_b32_e32 v132, 16, v74
	v_and_b32_e32 v133, 0xffff0000, v74
	v_lshlrev_b32_e32 v134, 16, v75
	v_and_b32_e32 v135, 0xffff0000, v75
	v_lshlrev_b32_e32 v136, 16, v76
	v_and_b32_e32 v137, 0xffff0000, v76
	v_lshlrev_b32_e32 v138, 16, v77
	v_and_b32_e32 v139, 0xffff0000, v77
	v_lshlrev_b32_e32 v140, 16, v78
	v_and_b32_e32 v141, 0xffff0000, v78
	v_lshlrev_b32_e32 v142, 16, v79
	v_and_b32_e32 v143, 0xffff0000, v79
	v_mul_f32_e32 v128, v9, v128
	v_mul_f32_e32 v129, v9, v129
	v_mul_f32_e32 v130, v9, v130
	v_mul_f32_e32 v131, v9, v131
	v_mul_f32_e32 v132, v9, v132
	v_mul_f32_e32 v133, v9, v133
	v_mul_f32_e32 v134, v9, v134
	v_mul_f32_e32 v135, v9, v135
	v_mul_f32_e32 v136, v9, v136
	v_mul_f32_e32 v137, v9, v137
	v_mul_f32_e32 v138, v9, v138
	v_mul_f32_e32 v139, v9, v139
	v_mul_f32_e32 v140, v9, v140
	v_mul_f32_e32 v141, v9, v141
	v_mul_f32_e32 v142, v9, v142
	v_mul_f32_e32 v143, v9, v143
	v_mul_f32_e32 v128, v10, v128
	v_mul_f32_e32 v129, v11, v129
	v_mul_f32_e32 v130, v12, v130
	v_mul_f32_e32 v131, v13, v131
	v_mul_f32_e32 v132, v14, v132
	v_mul_f32_e32 v133, v15, v133
	v_mul_f32_e32 v134, v16, v134
	v_mul_f32_e32 v135, v17, v135
	v_mul_f32_e32 v136, v18, v136
	v_mul_f32_e32 v137, v19, v137
	v_mul_f32_e32 v138, v20, v138
	v_mul_f32_e32 v139, v21, v139
	v_mul_f32_e32 v140, v22, v140
	v_mul_f32_e32 v141, v23, v141
	v_mul_f32_e32 v142, v24, v142
	v_mul_f32_e32 v143, v25, v143
	s_lshl_b32 s17, s16, 12
	s_add_u32 s18, s66, s17
	s_addc_u32 s19, s67, 0
	global_store_dwordx4 v0, v[128:131], s[18:19]
	global_store_dwordx4 v0, v[132:135], s[18:19] offset:1024
	global_store_dwordx4 v0, v[136:139], s[18:19] offset:2048
	global_store_dwordx4 v0, v[140:143], s[18:19] offset:3072
	s_add_i32 s16, s16, s58
	s_waitcnt vmcnt(16)
	v_add_f32_e32 v80, v80, v81
	v_add_f32_e32 v82, v82, v83
	v_add_f32_e32 v84, v84, v85
	v_add_f32_e32 v86, v86, v87
	v_add_f32_e32 v88, v88, v89
	v_add_f32_e32 v90, v90, v91
	v_add_f32_e32 v92, v92, v93
	v_add_f32_e32 v94, v94, v95
	v_add_f32_e32 v80, v80, v82
	v_add_f32_e32 v84, v84, v86
	v_add_f32_e32 v88, v88, v90
	v_add_f32_e32 v92, v92, v94
	v_add_f32_e32 v80, v80, v84
	v_add_f32_e32 v88, v88, v92
	v_add_f32_e32 v80, v80, v88
	v_fmamk_f32 v80, v80, 0x3a800000, v8
	v_rsq_f32_e32 v9, v80
	v_lshlrev_b32_e32 v128, 16, v96
	v_and_b32_e32 v129, 0xffff0000, v96
	v_lshlrev_b32_e32 v130, 16, v97
	v_and_b32_e32 v131, 0xffff0000, v97
	v_lshlrev_b32_e32 v132, 16, v98
	v_and_b32_e32 v133, 0xffff0000, v98
	v_lshlrev_b32_e32 v134, 16, v99
	v_and_b32_e32 v135, 0xffff0000, v99
	v_lshlrev_b32_e32 v136, 16, v100
	v_and_b32_e32 v137, 0xffff0000, v100
	v_lshlrev_b32_e32 v138, 16, v101
	v_and_b32_e32 v139, 0xffff0000, v101
	v_lshlrev_b32_e32 v140, 16, v102
	v_and_b32_e32 v141, 0xffff0000, v102
	v_lshlrev_b32_e32 v142, 16, v103
	v_and_b32_e32 v143, 0xffff0000, v103
	v_mul_f32_e32 v128, v9, v128
	v_mul_f32_e32 v129, v9, v129
	v_mul_f32_e32 v130, v9, v130
	v_mul_f32_e32 v131, v9, v131
	v_mul_f32_e32 v132, v9, v132
	v_mul_f32_e32 v133, v9, v133
	v_mul_f32_e32 v134, v9, v134
	v_mul_f32_e32 v135, v9, v135
	v_mul_f32_e32 v136, v9, v136
	v_mul_f32_e32 v137, v9, v137
	v_mul_f32_e32 v138, v9, v138
	v_mul_f32_e32 v139, v9, v139
	v_mul_f32_e32 v140, v9, v140
	v_mul_f32_e32 v141, v9, v141
	v_mul_f32_e32 v142, v9, v142
	v_mul_f32_e32 v143, v9, v143
	v_mul_f32_e32 v128, v10, v128
	v_mul_f32_e32 v129, v11, v129
	v_mul_f32_e32 v130, v12, v130
	v_mul_f32_e32 v131, v13, v131
	v_mul_f32_e32 v132, v14, v132
	v_mul_f32_e32 v133, v15, v133
	v_mul_f32_e32 v134, v16, v134
	v_mul_f32_e32 v135, v17, v135
	v_mul_f32_e32 v136, v18, v136
	v_mul_f32_e32 v137, v19, v137
	v_mul_f32_e32 v138, v20, v138
	v_mul_f32_e32 v139, v21, v139
	v_mul_f32_e32 v140, v22, v140
	v_mul_f32_e32 v141, v23, v141
	v_mul_f32_e32 v142, v24, v142
	v_mul_f32_e32 v143, v25, v143
	s_lshl_b32 s17, s16, 12
	s_add_u32 s18, s66, s17
	s_addc_u32 s19, s67, 0
	global_store_dwordx4 v0, v[128:131], s[18:19]
	global_store_dwordx4 v0, v[132:135], s[18:19] offset:1024
	global_store_dwordx4 v0, v[136:139], s[18:19] offset:2048
	global_store_dwordx4 v0, v[140:143], s[18:19] offset:3072
	s_add_i32 s16, s16, s58
	s_waitcnt vmcnt(12)
; __device__ __forceinline__ float row_rstd(const float* ss, int row) {
;     const f32x4* p = (const f32x4*)(ss + (size_t)row * 16); const f32x4 a = p[0], b = p[1], c = p[2], d = p[3];
;     const float s = (((a[0] + a[1]) + (a[2] + a[3])) + ((b[0] + b[1]) + (b[2] + b[3]))) + (((c[0] + c[1]) + (c[2] + c[3])) + ((d[0] + d[1]) + (d[2] + d[3])));
;     return __builtin_amdgcn_rsqf(s * (1.f / DM) + EPS);
; }
; __global__ void __launch_bounds__(NWAVES * 64, 2) mk_fwd(Args args) {
;     ...
;         for (int m = gw; m < MT; m += NGW) { const float rs = row_rstd(ss, m);
;             const u32x4* xr = (const u32x4*)(X3 + (size_t)m * DM) + lane; f32x4* orow = (f32x4*)(P.out + (size_t)m * DM); const f32x4* gr = (const f32x4*)P.g_fin;
; #pragma unroll
;             for (int j = 0; j < 2; ++j) { const u32x4 w = xr[64 * j]; const int c4 = (64 * j + lane) * 2; const f32x4 ga = gr[c4], gb = gr[c4 + 1];
;                 f32x4 a, b2; a[0] = bflo(w.x) * rs * ga[0]; a[1] = bfhi(w.x) * rs * ga[1]; a[2] = bflo(w.y) * rs * ga[2]; a[3] = bfhi(w.y) * rs * ga[3];
;                 b2[0] = bflo(w.z) * rs * gb[0]; b2[1] = bfhi(w.z) * rs * gb[1]; b2[2] = bflo(w.w) * rs * gb[2]; b2[3] = bfhi(w.w) * rs * gb[3];
;                 orow[c4] = a; orow[c4 + 1] = b2; } }
	v_add_f32_e32 v104, v104, v105
	v_add_f32_e32 v106, v106, v107
	v_add_f32_e32 v108, v108, v109
	v_add_f32_e32 v110, v110, v111
	v_add_f32_e32 v112, v112, v113
	v_add_f32_e32 v114, v114, v115
	v_add_f32_e32 v116, v116, v117
	v_add_f32_e32 v118, v118, v119
	v_add_f32_e32 v104, v104, v106
	v_add_f32_e32 v108, v108, v110
	v_add_f32_e32 v112, v112, v114
	v_add_f32_e32 v116, v116, v118
	v_add_f32_e32 v104, v104, v108
	v_add_f32_e32 v112, v112, v116
	v_add_f32_e32 v104, v104, v112
	v_fmamk_f32 v104, v104, 0x3a800000, v8
	v_rsq_f32_e32 v9, v104
	v_lshlrev_b32_e32 v128, 16, v120
	v_and_b32_e32 v129, 0xffff0000, v120
	v_lshlrev_b32_e32 v130, 16, v121
	v_and_b32_e32 v131, 0xffff0000, v121
	v_lshlrev_b32_e32 v132, 16, v122
	v_and_b32_e32 v133, 0xffff0000, v122
	v_lshlrev_b32_e32 v134, 16, v123
	v_and_b32_e32 v135, 0xffff0000, v123
	v_lshlrev_b32_e32 v136, 16, v124
	v_and_b32_e32 v137, 0xffff0000, v124
	v_lshlrev_b32_e32 v138, 16, v125
	v_and_b32_e32 v139, 0xffff0000, v125
	v_lshlrev_b32_e32 v140, 16, v126
	v_and_b32_e32 v141, 0xffff0000, v126
	v_lshlrev_b32_e32 v142, 16, v127
	v_and_b32_e32 v143, 0xffff0000, v127
	v_mul_f32_e32 v128, v9, v128
	v_mul_f32_e32 v129, v9, v129
	v_mul_f32_e32 v130, v9, v130
	v_mul_f32_e32 v131, v9, v131
	v_mul_f32_e32 v132, v9, v132
	v_mul_f32_e32 v133, v9, v133
	v_mul_f32_e32 v134, v9, v134
	v_mul_f32_e32 v135, v9, v135
	v_mul_f32_e32 v136, v9, v136
	v_mul_f32_e32 v137, v9, v137
	v_mul_f32_e32 v138, v9, v138
	v_mul_f32_e32 v139, v9, v139
	v_mul_f32_e32 v140, v9, v140
	v_mul_f32_e32 v141, v9, v141
	v_mul_f32_e32 v142, v9, v142
	v_mul_f32_e32 v143, v9, v143
	v_mul_f32_e32 v128, v10, v128
	v_mul_f32_e32 v129, v11, v129
	v_mul_f32_e32 v130, v12, v130
	v_mul_f32_e32 v131, v13, v131
	v_mul_f32_e32 v132, v14, v132
	v_mul_f32_e32 v133, v15, v133
	v_mul_f32_e32 v134, v16, v134
	v_mul_f32_e32 v135, v17, v135
	v_mul_f32_e32 v136, v18, v136
	v_mul_f32_e32 v137, v19, v137
	v_mul_f32_e32 v138, v20, v138
	v_mul_f32_e32 v139, v21, v139
	v_mul_f32_e32 v140, v22, v140
	v_mul_f32_e32 v141, v23, v141
	v_mul_f32_e32 v142, v24, v142
	v_mul_f32_e32 v143, v25, v143
	s_lshl_b32 s17, s16, 12
	s_add_u32 s18, s66, s17
	s_addc_u32 s19, s67, 0
	global_store_dwordx4 v0, v[128:131], s[18:19]
	global_store_dwordx4 v0, v[132:135], s[18:19] offset:1024
	global_store_dwordx4 v0, v[136:139], s[18:19] offset:2048
	global_store_dwordx4 v0, v[140:143], s[18:19] offset:3072
	s_lshl_b32 s17, s58, 2
	s_add_i32 s8, s8, s17
	s_mul_i32 s9, s58, 3
	s_add_i32 s9, s9, s8
	s_cmpk_lt_i32 s9, 0x4000
	s_cbranch_scc1 .Lp9_loop
.Lp9_tail:
	s_sub_i32 s0, s8, s1
	s_add_i32 s8, s0, s1
	s_cmpk_gt_i32 s8, 0x3fff
	s_cbranch_scc1 .LBB0_1155
	s_ashr_i32 s2, s0, 31
	s_ashr_i32 s3, s1, 31
	s_add_u32 s6, s0, s1
	s_addc_u32 s7, s2, s3
	s_ashr_i32 s59, s58, 31
	s_lshl_b64 s[0:1], s[6:7], 6
	s_lshl_b64 s[2:3], s[58:59], 6
	s_lshl_b64 s[4:5], s[6:7], 12
	v_and_b32_e32 v6, 63, v185
	s_add_u32 s4, s66, s4
	v_lshlrev_b32_e32 v0, 5, v6
	s_waitcnt lgkmcnt(0)
	v_mov_b32_e32 v1, 0
	s_addc_u32 s5, s67, s5
	v_lshl_add_u64 v[4:5], s[4:5], 0, v[0:1]
	s_mov_b64 s[4:5], 0x810
	s_lshl_b64 s[6:7], s[6:7], 11
	v_lshl_add_u64 v[2:3], s[64:65], 0, v[0:1]
	v_lshl_add_u64 v[4:5], v[4:5], 0, s[4:5]
	s_lshl_b64 s[4:5], s[58:59], 12
	v_lshl_or_b32 v6, v6, 4, s6
	v_mov_b32_e32 v7, s7
	s_lshl_b64 s[6:7], s[58:59], 11
	v_mov_b32_e32 v0, 0x400000
	v_mov_b32_e32 v8, 0x358637bd
	s_mov_b32 s9, 0x3800000
